# XCD-local barriers invalidate only the vector L1 (buffer_inv sc0) instead of L1+L2 (sc1)
# speedup vs baseline: 1.0040x; 1.0040x over previous
.LBB0_725:
	s_or_b64 exec, exec, s[14:15]
	s_waitcnt lgkmcnt(0)
	v_readlane_b32 s2, v255, 40
	s_nop 0
	s_cmp_lg_u32 s2, 0
	s_cbranch_scc1 .Linv0_b3n
	buffer_inv sc1
	s_branch .Linv1_b3n
.Linv0_b3n:
	buffer_inv sc0
.Linv1_b3n:
	s_waitcnt vmcnt(0)
.LBB0_726:
	s_andn2_saveexec_b64 s[2:3], s[10:11]
	s_cbranch_execz .LBB0_759
	s_mov_b64 s[10:11], exec
	v_readlane_b32 s2, v255, 40
	s_nop 0
	s_cmp_lg_u32 s2, 0
	s_cbranch_scc1 .LBB0_756
	buffer_wbl2 sc1
	s_waitcnt lgkmcnt(0)
	s_waitcnt vmcnt(0)
	v_mbcnt_lo_u32_b32 v0, s10, 0
	v_mbcnt_hi_u32_b32 v0, s11, v0
	v_cmp_eq_u32_e32 vcc, 0, v0
	s_and_saveexec_b64 s[12:13], vcc
	s_cbranch_execz .LBB0_729
	s_bcnt1_i32_b64 s2, s[10:11]
	v_mov_b32_e32 v3, s2
	global_atomic_add v3, v254, v3, s[6:7] offset:1024 sc0

.LBB0_756:
	s_or_b64 exec, exec, s[10:11]
	s_mov_b64 s[6:7], exec
	v_mbcnt_lo_u32_b32 v0, s6, 0
	v_mbcnt_hi_u32_b32 v0, s7, v0
	v_cmp_eq_u32_e32 vcc, 0, v0
	s_waitcnt vmcnt(0)
	v_readlane_b32 s2, v255, 40
	s_nop 0
	s_cmp_lg_u32 s2, 0
	s_cbranch_scc1 .Linv0_b3j
	buffer_inv sc1
	s_branch .Linv1_b3j

.Linv1_b3j:
	s_and_saveexec_b64 s[10:11], vcc
	s_cbranch_execz .LBB0_758
	s_bcnt1_i32_b64 s2, s[6:7]
	v_mov_b32_e32 v0, s2
	global_atomic_add v231, v0, s[8:9] offset:1024

.Linv1_b4n:
	s_waitcnt vmcnt(0)
.LBB0_800:
	s_andn2_saveexec_b64 s[2:3], s[10:11]
	s_cbranch_execz .LBB0_833
	s_mov_b64 s[10:11], exec
	v_readlane_b32 s2, v255, 40
	s_nop 0
	s_cmp_lg_u32 s2, 0
	s_cbranch_scc1 .LBB0_830
	buffer_wbl2 sc1
	s_waitcnt lgkmcnt(0)
	s_waitcnt vmcnt(0)
	v_mbcnt_lo_u32_b32 v0, s10, 0
	v_mbcnt_hi_u32_b32 v0, s11, v0
	v_cmp_eq_u32_e32 vcc, 0, v0
	s_and_saveexec_b64 s[12:13], vcc
	s_cbranch_execz .LBB0_803
	s_bcnt1_i32_b64 s2, s[10:11]
	v_mov_b32_e32 v3, s2
	global_atomic_add v3, v254, v3, s[6:7] offset:1024 sc0

.Linv1_b5n:
	s_waitcnt vmcnt(0)
.LBB0_921:
	s_andn2_saveexec_b64 s[2:3], s[10:11]
	s_cbranch_execz .LBB0_954
	s_mov_b64 s[10:11], exec
	v_readlane_b32 s2, v255, 40
	s_nop 0
	s_cmp_lg_u32 s2, 0
	s_cbranch_scc1 .LBB0_951
	buffer_wbl2 sc1
	s_waitcnt lgkmcnt(0)
	s_waitcnt vmcnt(0)
	v_mbcnt_lo_u32_b32 v0, s10, 0
	v_mbcnt_hi_u32_b32 v0, s11, v0
	v_cmp_eq_u32_e32 vcc, 0, v0
	s_and_saveexec_b64 s[12:13], vcc
	s_cbranch_execz .LBB0_924
	s_bcnt1_i32_b64 s2, s[10:11]
	v_mov_b32_e32 v3, s2
	global_atomic_add v3, v254, v3, s[6:7] offset:1024 sc0

.LBB0_1138:
	s_or_b64 exec, exec, s[16:17]
	s_waitcnt lgkmcnt(0)
	v_readlane_b32 s2, v255, 40
	s_nop 0
	s_cmp_lg_u32 s2, 0
	s_cbranch_scc1 .Linv0_b1n
	buffer_inv sc1
	s_branch .Linv1_b1n

.Linv1_b1n:
	s_waitcnt vmcnt(0)
.LBB0_1139:
	s_andn2_saveexec_b64 s[2:3], s[12:13]
	s_cbranch_execz .LBB0_1172
	s_mov_b64 s[12:13], exec
	v_readlane_b32 s2, v255, 40
	s_nop 0
	s_cmp_lg_u32 s2, 0
	s_cbranch_scc1 .LBB0_1169
	buffer_wbl2 sc1
	s_waitcnt lgkmcnt(0)
	s_waitcnt vmcnt(0)
	v_mbcnt_lo_u32_b32 v0, s12, 0
	v_mbcnt_hi_u32_b32 v0, s13, v0
	v_cmp_eq_u32_e32 vcc, 0, v0
	s_and_saveexec_b64 s[14:15], vcc
	s_cbranch_execz .LBB0_1142
	s_bcnt1_i32_b64 s2, s[12:13]
	v_mov_b32_e32 v3, s2
	global_atomic_add v3, v254, v3, s[6:7] offset:1024 sc0

.LBB0_1169:
	s_or_b64 exec, exec, s[12:13]
	s_mov_b64 s[6:7], exec
	v_mbcnt_lo_u32_b32 v0, s6, 0
	v_mbcnt_hi_u32_b32 v0, s7, v0
	v_cmp_eq_u32_e32 vcc, 0, v0
	s_waitcnt vmcnt(0)
	v_readlane_b32 s2, v255, 40
	s_nop 0
	s_cmp_lg_u32 s2, 0
	s_cbranch_scc1 .Linv0_b1j
	buffer_inv sc1
	s_branch .Linv1_b1j

.Linv1_b1j:
	s_and_saveexec_b64 s[12:13], vcc
	s_cbranch_execz .LBB0_1171
	s_bcnt1_i32_b64 s2, s[6:7]
	v_mov_b32_e32 v0, s2
	global_atomic_add v231, v0, s[8:9] offset:1024
